# ctxsum phase folded into the wout-GEMM phase: publish counter + acquire for the 32 context-unit blocks replaces one grid barrier per layer
# baseline (speedup 1.0000x reference)
; #define PG8_STAGE(bufoff, gbase, voff) do { _Pragma("unroll") for (int _i = 0; _i < 2; ++_i) \
;         __builtin_amdgcn_global_load_lds((const unsigned*)((const char*)(gbase) + (voff)[_i]), (LAS unsigned*)(lds + (bufoff) + ldsw + _i * 8192), 16, 0, 0); } while (0)
; #define PG8_WAIT_V(n) asm volatile("s_waitcnt vmcnt(" #n ")" ::: "memory")
; #define PG8_BAR __builtin_amdgcn_s_barrier()
; template <class Epi, class Sched>
; __device__ __forceinline__ void gemm_phase(LAS unsigned char* lds, const Gemm g, const Sched& S, const Epi& E, const int tid) {
;     ...
;     for (int i = 0; i < 2; ++i) { int R, C; stage_rc(tid * 16 + i * 8192, R, C); const int Rb = Epi::PERM ? ((R & ~31) + perm32(R & 31)) : R;
;         voffA[i] = (unsigned)(R * lda + C) * 2u; voffB[i] = (unsigned)(Rb * K + C) * 2u; }
;     const size_t kstep = (size_t)(BK * 2);
;     const size_t hstepA = (size_t)HALF * lda * 2, hstepB = (size_t)HALF * K * 2;
;     const size_t tstepA = 2 * hstepA, tstepB = 2 * hstepB;
;     const unsigned ldsw = (unsigned)wid * 1024u;
;     const int aoff = lds_byte(wr * 64 + fr, fq * 8), boff = lds_byte(wc * 32 + fr, fq * 8);
;     ...
;     Unit cur, nxt; int ui = 0;
;     if (!S.next(0, cur)) return;
;     f32x4 acc[2][2][4][2];
; #pragma unroll
;     for (int a = 0; a < 2; ++a)
; #pragma unroll
;         for (int b = 0; b < 2; ++b)
; #pragma unroll
;             for (int m = 0; m < 4; ++m)
; #pragma unroll
;                 for (int n = 0; n < 2; ++n) acc[a][b][m][n] = (f32x4){0.f, 0.f, 0.f, 0.f};
;     bf16x8 At[4][2], B0[2][2], B1[2][2];
;     const char* cA = PG8_UA(cur); const char* cB = PG8_UB(cur);
;     PG8_STAGE(PG8_SB(0, 0), cB, voffB); PG8_STAGE(PG8_SB(0, 1), cB + hstepB, voffB); PG8_STAGE(PG8_SA(0, 0), cA, voffA); PG8_STAGE(PG8_SA(0, 1), cA + hstepA, voffA);
;     if (wr == 1) PG8_BAR;
;     PG8_WAIT_V(2); PG8_BAR;
;     PG8_STAGE(PG8_SB(1, 0), cB + kstep, voffB); PG8_STAGE(PG8_SA(1, 0), cA + kstep, voffA); PG8_STAGE(PG8_SB(1, 1), cB + hstepB + kstep, voffB);
.LBB0_87:
	s_and_b64 vcc, exec, s[4:5]
	s_cbranch_vccz .LBB0_170
	s_cmp_gt_u32 s60, 31
	s_cbranch_scc1 .Lcw_done
	v_readfirstlane_b32 s2, v166
	s_cmp_lg_u32 s2, 0
	s_cbranch_scc1 .Lcw_bar
	v_readlane_b32 s2, v253, 17
	s_add_i32 s2, s2, 3
	s_mul_i32 s2, s2, 0x124a
	s_lshr_b32 s2, s2, 16
	s_lshl_b32 s2, s2, 6
	s_add_u32 s22, s14, 0x3800
	s_addc_u32 s23, s15, 0
	s_mov_b64 s[8:9], exec
	s_mov_b64 exec, 1
.Lcw_spin:
	global_load_dword v2, v1, s[22:23] sc1
	s_waitcnt vmcnt(0)
	v_readfirstlane_b32 s28, v2
	s_cmp_lt_u32 s28, s2
	s_cbranch_scc0 .Lcw_got
	s_sleep 1
	s_branch .Lcw_spin
.Lcw_got:
	buffer_inv sc1
	s_waitcnt vmcnt(0)
	s_mov_b64 exec, s[8:9]
.Lcw_bar:
	s_barrier
.Lcw_done:
	v_mov_b32_e32 v15, v166
	s_cmpk_gt_i32 s60, 0x11f
	s_nop 0
	v_readfirstlane_b32 s4, v15
	s_cbranch_scc1 .LBB0_170
	v_lshlrev_b32_e32 v2, 4, v15
	v_add_u32_e32 v3, 0x2000, v2
	v_ashrrev_i32_e32 v0, 31, v3
	v_lshrrev_b32_e32 v0, 22, v0
	v_add_u32_e32 v0, v3, v0
	v_ashrrev_i32_e32 v0, 10, v0
	v_mul_i32_i24_e32 v4, 0x400, v0
	v_sub_u32_e32 v3, v3, v4
	v_lshrrev_b32_e32 v4, 4, v3
	v_bitop3_b32 v3, v4, v3, 32 bitop3:0x6c
	v_ashrrev_i32_e32 v4, 31, v3
	v_lshrrev_b32_e32 v4, 26, v4
	s_ashr_i32 s2, s4, 6
	v_add_u32_e32 v4, v3, v4
	s_ashr_i32 s5, s4, 8
	s_lshl_b32 s28, s2, 10
	v_readlane_b32 s6, v253, 1
	v_ashrrev_i32_e32 v10, 6, v4
	v_and_b32_e32 v4, 0xc0, v4
	s_add_u32 s29, s6, 0x2000000
	v_readlane_b32 s6, v253, 2
	v_sub_u32_e32 v3, v3, v4
	s_addc_u32 s33, s6, 0
	s_add_i32 s6, s60, 0xffffff00
	v_lshlrev_b32_e32 v5, 3, v0
	v_lshlrev_b32_e32 v6, 5, v0
	v_ashrrev_i16_sdwa v3, v203, sext(v3) dst_sel:DWORD dst_unused:UNUSED_PAD src0_sel:DWORD src1_sel:BYTE_0
	s_lshr_b32 s6, s6, 1
	v_readlane_b32 s8, v253, 3
	v_and_b32_e32 v5, 0x1ffff0, v5
	v_and_b32_e32 v6, 32, v6
	v_bfe_i32 v11, v3, 0, 16
	s_and_b32 s20, s6, 0x7ffffffe
	v_readlane_b32 s9, v253, 4
	v_add_u32_e32 v3, v6, v11
	v_add_lshl_u32 v4, v10, v5, 11
	s_and_b64 s[6:7], s[8:9], exec
	s_waitcnt vmcnt(0)
	v_lshl_add_u32 v134, v3, 1, v4
	v_bfe_i32 v3, v15, 27, 1
	s_cselect_b32 s38, 0, s20
	v_lshrrev_b32_e32 v3, 22, v3
	s_lshl_b32 s20, s16, 19
	s_lshl_b64 s[6:7], s[38:39], 7
	s_lshl_b32 s22, s3, 19
	v_add_u32_e32 v3, v2, v3
	s_add_u32 s22, s29, s22
	v_and_b32_e32 v3, 0xfffffc00, v3
	s_addc_u32 s23, s33, 0
	v_sub_u32_e32 v2, v2, v3
	s_add_u32 s54, s22, s6
	v_lshrrev_b32_e32 v3, 4, v2
	s_addc_u32 s55, s23, s7
	v_bitop3_b32 v2, v3, v2, 32 bitop3:0x6c
	s_add_u32 s20, s84, s20
	v_ashrrev_i32_e32 v3, 31, v2
	s_addc_u32 s24, s85, 0
	v_lshrrev_b32_e32 v3, 26, v3
	v_ashrrev_i32_e32 v4, 31, v15
	s_add_u32 s22, s54, 0x40000
	v_add_u32_e32 v3, v2, v3
	v_lshrrev_b32_e32 v4, 26, v4
	s_addc_u32 s23, s55, 0
	v_ashrrev_i32_e32 v12, 6, v3
	v_add_u32_e32 v4, v15, v4
	v_and_b32_e32 v3, 0xc0, v3
	s_add_u32 s48, s20, s6
	v_ashrrev_i32_e32 v13, 6, v4
	v_sub_u32_e32 v2, v2, v3
	s_addc_u32 s49, s24, s7
	v_lshlrev_b32_e32 v4, 3, v13
	v_lshlrev_b32_e32 v5, 5, v13
	v_ashrrev_i16_sdwa v2, v203, sext(v2) dst_sel:DWORD dst_unused:UNUSED_PAD src0_sel:DWORD src1_sel:BYTE_0
	s_add_u32 s6, s48, 0x40000
	v_and_b32_e32 v4, 0x1ffff0, v4
	v_and_b32_e32 v5, 32, v5
	v_bfe_i32 v14, v2, 0, 16
	s_addc_u32 s7, s49, 0
	v_add_u32_e32 v2, v5, v14
	v_add_lshl_u32 v3, v12, v4, 11
	s_add_i32 s56, s28, 0
	v_lshl_add_u32 v136, v2, 1, v3
	s_add_i32 m0, s56, 0x10000
	s_add_i32 s62, s56, 0x2000
	global_load_lds_dwordx4 v136, s[54:55]
	s_add_i32 m0, s56, 0x12000
	s_add_i32 s63, s56, 0x4000
	global_load_lds_dwordx4 v134, s[54:55]
	s_add_i32 m0, s56, 0x14000
	s_add_i32 s64, s56, 0x6000
	global_load_lds_dwordx4 v136, s[22:23]
	s_add_i32 m0, s56, 0x16000
	v_mov_b32_e32 v137, v1
	global_load_lds_dwordx4 v134, s[22:23]
	s_mov_b32 m0, s56
	v_mov_b32_e32 v135, v1
	global_load_lds_dwordx4 v136, s[48:49]
	s_mov_b32 m0, s62
	s_cmp_eq_u32 s5, 1
	global_load_lds_dwordx4 v134, s[48:49]
	s_mov_b32 m0, s63
	s_mov_b64 s[70:71], s[52:53]
	global_load_lds_dwordx4 v136, s[6:7]
	s_mov_b32 m0, s64
	s_mov_b64 s[68:69], s[46:47]
	global_load_lds_dwordx4 v134, s[6:7]
	v_lshl_add_u64 v[8:9], s[54:55], 0, v[136:137]
	v_lshl_add_u64 v[6:7], s[54:55], 0, v[134:135]
	v_lshl_add_u64 v[2:3], s[48:49], 0, v[136:137]
	s_cselect_b64 s[6:7], -1, 0
	s_cmp_lg_u32 s5, 1
	v_lshl_add_u64 v[4:5], s[48:49], 0, v[134:135]
	s_cbranch_scc1 .LBB0_91
	s_barrier

; __device__ __forceinline__ unsigned pk2(float lo, float hi) { const f32x2_t v = {lo, hi}; const bf16x2_t b = __builtin_convertvector(v, bf16x2_t); return __builtin_bit_cast(unsigned, b); }
; __device__ __forceinline__ void ctxsum_phase(const Ctx& F, const float* part, bf16_t* MG) {
;     for (int i = F.bid * 512 + F.tid; i < CTX * 128; i += F.G * 512) {
;         const int r = i >> 7, c8 = (i & 127) * 8;
;         const float* p = part + (size_t)r * D + c8;
;         f32x4 a0 = *(const f32x4*)p, a1 = *(const f32x4*)(p + 4);
; #pragma unroll
;         for (int b = 1; b < 4; ++b) { a0 += *(const f32x4*)(p + (size_t)b * 256 * D); a1 += *(const f32x4*)(p + (size_t)b * 256 * D + 4); }
;         u32x4 w; w.x = pk2(a0[0], a0[1]); w.y = pk2(a0[2], a0[3]); w.z = pk2(a1[0], a1[1]); w.w = pk2(a1[2], a1[3]);
;         *(u32x4*)(MG + (size_t)(SEQ + r) * D + c8) = w;
;     }
; }
.LBB0_176:
	s_or_b64 exec, exec, s[4:5]
	s_waitcnt vmcnt(0)
	s_barrier
	v_readfirstlane_b32 s2, v166
	s_cmp_lg_u32 s2, 0
	s_cbranch_scc1 .Lcs_done
	s_cmp_gt_u32 s60, 63
	s_cbranch_scc1 .Lcs_done
	buffer_wbl2 sc1
	s_waitcnt vmcnt(0)
	s_add_u32 s22, s14, 0x3800
	s_addc_u32 s23, s15, 0
	s_mov_b64 s[26:27], exec
	s_mov_b64 exec, 1
	v_mov_b32_e32 v2, 1
	global_atomic_add v1, v2, s[22:23]
	s_mov_b64 exec, s[26:27]
.Lcs_done:
	s_mov_b64 s[4:5], 0
.LBB0_177:
	s_andn2_b64 vcc, exec, s[4:5]
	s_cbranch_vccnz .LBB0_290
	v_readlane_b32 s4, v253, 3
	v_readlane_b32 s5, v253, 4
	v_mov_b32_e32 v0, v166
	s_andn2_b64 vcc, exec, s[4:5]
	s_mov_b32 s38, 0
	s_cbranch_vccnz .LBB0_180
	v_readlane_b32 s2, v251, 15
	s_sub_i32 s2, s2, s60
	s_ashr_i32 s4, s2, 31
	s_abs_i32 s2, s2
	v_readlane_b32 s5, v252, 7
	s_mul_hi_u32 s5, s2, s5
	v_readlane_b32 s20, v252, 6
	s_mul_i32 s6, s5, s20
	s_sub_i32 s2, s2, s6
	s_xor_b32 s4, s4, s19
	s_add_i32 s6, s5, 1
	s_sub_i32 s7, s2, s20
	s_cmp_ge_u32 s2, s20
	s_cselect_b32 s5, s6, s5
	s_cselect_b32 s2, s7, s2
	s_add_i32 s6, s5, 1
	s_cmp_ge_u32 s2, s20
	s_cselect_b32 s2, s6, s5
	s_xor_b32 s2, s2, s4
	s_sub_i32 s2, s2, s4
	s_lshl_b32 s38, s2, 2

; __global__ void __launch_bounds__(512, 2) mk_fwd(Args args) {
;     ...
;         if (ph + 1 < args.ph_hi) { if (ph == 0) grid.sync(); else xcd_barrier(xbar); if (PROBE_DBL & 128) xcd_barrier(xbar); }
.LBB0_724:
	s_mov_b32 s2, 0x1000400
	s_mov_b32 s3, 0x100040
	s_bitcmp1_b64 s[2:3], s33
	s_cbranch_scc0 .Lcs_bar
	s_mov_b64 s[4:5], 0
	s_branch .LBB0_778
